# LRU tile loop: tile 1's conv-window loads prefetched into spare VGPRs during tile 0
# baseline (speedup 1.0000x reference)
; __device__ __forceinline__ float bf2f(bf16 b) { return __uint_as_float((unsigned)b << 16); }
; __device__ __forceinline__ void lru_unit(const Ctx& C, const Params& p, int l, int unit) {
;     ...
;         const int tl0 = tile * 128 + 16 * tg, t0 = tc * 256 + tl0;
;         float xw[19], gbv[16], xc[16];
; #pragma unroll
;         for (int k = 0; k < 19; ++k) { const int t = t0 - 3 + k; xw[k] = (t >= 0) ? bf2f(Zb[(size_t)t * ZC + XB + ch]) : 0.f; }
.LBB0_327:
	v_add_u32_e32 v71, s24, v125
	v_add_u32_e32 v73, s21, v71
	v_lshlrev_b32_e32 v192, 1, v114
	v_mov_b64_e32 v[112:113], s[50:51]
	v_lshl_add_u64 v[112:113], v[112:113], 0, v[192:193]
	v_add_co_u32_e32 v112, vcc, 0x1000, v112
	v_add_u32_e32 v65, -3, v73
	v_add_u32_e32 v64, -2, v73
	v_addc_co_u32_e32 v113, vcc, 0, v113, vcc
	v_add_u32_e32 v67, -1, v73
	v_max_i32_e32 v65, 0, v65
	v_max_i32_e32 v64, 0, v64
	v_max_i32_e32 v67, 0, v67
	v_or_b32_e32 v74, 1, v73
	v_or_b32_e32 v79, 2, v73
	v_or_b32_e32 v80, 3, v73
	v_or_b32_e32 v81, 4, v73
	v_or_b32_e32 v84, 5, v73
	v_or_b32_e32 v86, 6, v73
	v_or_b32_e32 v92, 7, v73
	v_or_b32_e32 v87, 8, v73
	v_or_b32_e32 v93, 9, v73
	v_or_b32_e32 v98, 10, v73
	v_or_b32_e32 v99, 11, v73
	v_or_b32_e32 v104, 12, v73
	v_or_b32_e32 v105, 13, v73
	v_or_b32_e32 v108, 14, v73
	v_or_b32_e32 v110, 15, v73
	s_cmp_lg_u32 s24, 0
	s_cbranch_scc1 .Llru_t1
	v_mad_u64_u32 v[150:151], s[22:23], v65, s33, v[112:113]
	global_load_ushort v65, v[150:151], off offset:512
	v_mad_u64_u32 v[152:153], s[22:23], v64, s33, v[112:113]
	global_load_ushort v64, v[152:153], off offset:512
	v_mad_u64_u32 v[150:151], s[22:23], v67, s33, v[112:113]
	global_load_ushort v67, v[150:151], off offset:512
	v_mad_u64_u32 v[152:153], s[22:23], v73, s33, v[112:113]
	global_load_ushort v66, v[152:153], off offset:512
	v_mad_u64_u32 v[150:151], s[22:23], v74, s33, v[112:113]
	global_load_ushort v69, v[150:151], off offset:512
	v_mad_u64_u32 v[152:153], s[22:23], v79, s33, v[112:113]
	global_load_ushort v68, v[152:153], off offset:512
	v_mad_u64_u32 v[150:151], s[22:23], v80, s33, v[112:113]
	global_load_ushort v72, v[150:151], off offset:512
	v_mad_u64_u32 v[152:153], s[22:23], v81, s33, v[112:113]
	global_load_ushort v70, v[152:153], off offset:512
	v_mad_u64_u32 v[150:151], s[22:23], v84, s33, v[112:113]
	global_load_ushort v76, v[150:151], off offset:512
	v_mad_u64_u32 v[152:153], s[22:23], v86, s33, v[112:113]
	global_load_ushort v75, v[152:153], off offset:512
	v_mad_u64_u32 v[150:151], s[22:23], v92, s33, v[112:113]
	global_load_ushort v82, v[150:151], off offset:512
	v_mad_u64_u32 v[152:153], s[22:23], v87, s33, v[112:113]
	global_load_ushort v78, v[152:153], off offset:512
	v_mad_u64_u32 v[150:151], s[22:23], v93, s33, v[112:113]
	global_load_ushort v90, v[150:151], off offset:512
	v_mad_u64_u32 v[152:153], s[22:23], v98, s33, v[112:113]
	global_load_ushort v88, v[152:153], off offset:512
	v_mad_u64_u32 v[150:151], s[22:23], v99, s33, v[112:113]
	global_load_ushort v96, v[150:151], off offset:512
	v_mad_u64_u32 v[152:153], s[22:23], v104, s33, v[112:113]
	global_load_ushort v94, v[152:153], off offset:512
	v_mad_u64_u32 v[150:151], s[22:23], v105, s33, v[112:113]
	global_load_ushort v102, v[150:151], off offset:512
	v_mad_u64_u32 v[152:153], s[22:23], v108, s33, v[112:113]
	global_load_ushort v100, v[152:153], off offset:512
	v_mad_u64_u32 v[150:151], s[22:23], v110, s33, v[112:113]
	global_load_ushort v106, v[150:151], off offset:512
	v_add_u32_e32 v153, 125, v73
	v_mad_u64_u32 v[150:151], s[22:23], v153, s33, v[112:113]
	global_load_ushort v209, v[150:151], off offset:512
	v_add_u32_e32 v153, 126, v73
	v_mad_u64_u32 v[150:151], s[22:23], v153, s33, v[112:113]
	global_load_ushort v210, v[150:151], off offset:512
	v_add_u32_e32 v153, 127, v73
	v_mad_u64_u32 v[150:151], s[22:23], v153, s33, v[112:113]
	global_load_ushort v211, v[150:151], off offset:512
	v_add_u32_e32 v153, 128, v73
	v_mad_u64_u32 v[150:151], s[22:23], v153, s33, v[112:113]
	global_load_ushort v212, v[150:151], off offset:512
	v_add_u32_e32 v153, 129, v73
	v_mad_u64_u32 v[150:151], s[22:23], v153, s33, v[112:113]
	global_load_ushort v213, v[150:151], off offset:512
	v_add_u32_e32 v153, 130, v73
	v_mad_u64_u32 v[150:151], s[22:23], v153, s33, v[112:113]
	global_load_ushort v214, v[150:151], off offset:512
	v_add_u32_e32 v153, 131, v73
	v_mad_u64_u32 v[150:151], s[22:23], v153, s33, v[112:113]
	global_load_ushort v215, v[150:151], off offset:512
	v_add_u32_e32 v153, 132, v73
	v_mad_u64_u32 v[150:151], s[22:23], v153, s33, v[112:113]
	global_load_ushort v216, v[150:151], off offset:512
	v_add_u32_e32 v153, 133, v73
	v_mad_u64_u32 v[150:151], s[22:23], v153, s33, v[112:113]
	global_load_ushort v217, v[150:151], off offset:512
	v_add_u32_e32 v153, 134, v73
	v_mad_u64_u32 v[150:151], s[22:23], v153, s33, v[112:113]
	global_load_ushort v218, v[150:151], off offset:512
	v_add_u32_e32 v153, 135, v73
	v_mad_u64_u32 v[150:151], s[22:23], v153, s33, v[112:113]
	global_load_ushort v219, v[150:151], off offset:512
	v_add_u32_e32 v153, 136, v73
	v_mad_u64_u32 v[150:151], s[22:23], v153, s33, v[112:113]
	global_load_ushort v220, v[150:151], off offset:512
	v_add_u32_e32 v153, 137, v73
	v_mad_u64_u32 v[150:151], s[22:23], v153, s33, v[112:113]
	global_load_ushort v221, v[150:151], off offset:512
	v_add_u32_e32 v153, 138, v73
	v_mad_u64_u32 v[150:151], s[22:23], v153, s33, v[112:113]
	global_load_ushort v222, v[150:151], off offset:512
	v_add_u32_e32 v153, 139, v73
	v_mad_u64_u32 v[150:151], s[22:23], v153, s33, v[112:113]
	global_load_ushort v223, v[150:151], off offset:512
	v_add_u32_e32 v153, 140, v73
	v_mad_u64_u32 v[150:151], s[22:23], v153, s33, v[112:113]
	global_load_ushort v224, v[150:151], off offset:512
	v_add_u32_e32 v153, 141, v73
	v_mad_u64_u32 v[150:151], s[22:23], v153, s33, v[112:113]
	global_load_ushort v225, v[150:151], off offset:512
	v_add_u32_e32 v153, 142, v73
	v_mad_u64_u32 v[150:151], s[22:23], v153, s33, v[112:113]
	global_load_ushort v226, v[150:151], off offset:512
	v_add_u32_e32 v153, 143, v73
	v_mad_u64_u32 v[150:151], s[22:23], v153, s33, v[112:113]
	global_load_ushort v227, v[150:151], off offset:512
	s_waitcnt vmcnt(19)
	s_branch .Llru_conv
; #define LAS __attribute__((address_space(3)))
; __device__ __forceinline__ float bf2f(bf16 b) { return __uint_as_float((unsigned)b << 16); }
; __device__ __forceinline__ bf16 f2bf_hw(float x) { return (bf16)(pk2(x, x) & 0xffffu); }
; __device__ __forceinline__ void lru_unit(const Ctx& C, const Params& p, int l, int unit) {
;     ...
;         for (int k = 0; k < 19; ++k) { const int t = t0 - 3 + k; xw[k] = (t >= 0) ? bf2f(Zb[(size_t)t * ZC + XB + ch]) : 0.f; }
; #pragma unroll
;         for (int i = 0; i < 16; ++i) gbv[i] = bf2f(Zb[(size_t)(t0 + i) * ZC + GB + ch]);
; #pragma unroll
;         for (int i = 0; i < 16; ++i) { xc[i] = cb + cw0 * xw[i] + cw1 * xw[i + 1] + cw2 * xw[i + 2] + cw3 * xw[i + 3];
;             *(LAS bf16*)(XCB + (16 * tg + i) * 144 + c * 2) = f2bf_hw(xc[i]); }
.Llru_t1:
	s_waitcnt vmcnt(0)
	v_mov_b32_e32 v65, v209
	v_mov_b32_e32 v64, v210
	v_mov_b32_e32 v67, v211
	v_mov_b32_e32 v66, v212
	v_mov_b32_e32 v69, v213
	v_mov_b32_e32 v68, v214
	v_mov_b32_e32 v72, v215
	v_mov_b32_e32 v70, v216
	v_mov_b32_e32 v76, v217
	v_mov_b32_e32 v75, v218
	v_mov_b32_e32 v82, v219
	v_mov_b32_e32 v78, v220
	v_mov_b32_e32 v90, v221
	v_mov_b32_e32 v88, v222
	v_mov_b32_e32 v96, v223
	v_mov_b32_e32 v94, v224
	v_mov_b32_e32 v102, v225
	v_mov_b32_e32 v100, v226
	v_mov_b32_e32 v106, v227
.Llru_conv:
	v_cmp_ne_u32_e32 vcc, 0, v73
	v_lshlrev_b32_e32 v65, 16, v65
	v_lshlrev_b32_e32 v64, 16, v64
	v_lshlrev_b32_e32 v67, 16, v67
	v_cndmask_b32_e32 v65, 0, v65, vcc
	v_cndmask_b32_e32 v64, 0, v64, vcc
	v_cndmask_b32_e32 v67, 0, v67, vcc
	v_lshlrev_b32_e32 v66, 16, v66
	v_lshlrev_b32_e32 v69, 16, v69
	v_lshlrev_b32_e32 v68, 16, v68
	v_lshlrev_b32_e32 v72, 16, v72
	v_lshlrev_b32_e32 v70, 16, v70
	v_lshlrev_b32_e32 v76, 16, v76
	v_lshlrev_b32_e32 v75, 16, v75
	v_lshlrev_b32_e32 v82, 16, v82
	v_lshlrev_b32_e32 v78, 16, v78
	v_lshlrev_b32_e32 v90, 16, v90
	v_lshlrev_b32_e32 v88, 16, v88
	v_lshlrev_b32_e32 v96, 16, v96
	v_lshlrev_b32_e32 v94, 16, v94
	v_lshlrev_b32_e32 v102, 16, v102
	v_lshlrev_b32_e32 v100, 16, v100
	v_lshlrev_b32_e32 v106, 16, v106
	v_mov_b64_e32 v[112:113], s[50:51]
	v_mad_i64_i32 v[150:151], s[22:23], v73, s33, v[112:113]
	v_lshl_add_u64 v[150:151], v[150:151], 0, v[192:193]
	v_add_co_u32_e32 v150, vcc, 0x1000, v150
	s_nop 1
	v_addc_co_u32_e32 v151, vcc, 0, v151, vcc
	global_load_ushort v73, v[150:151], off offset:1536
	v_mad_i64_i32 v[150:151], s[22:23], v74, s33, v[112:113]
	v_lshl_add_u64 v[150:151], v[150:151], 0, v[192:193]
	v_add_co_u32_e32 v150, vcc, 0x1000, v150
	v_fma_f32 v74, v115, v69, v119
	s_nop 0
	v_addc_co_u32_e32 v151, vcc, 0, v151, vcc
	global_load_ushort v77, v[150:151], off offset:1536
	v_mad_i64_i32 v[150:151], s[22:23], v79, s33, v[112:113]
	v_lshl_add_u64 v[150:151], v[150:151], 0, v[192:193]
	v_add_co_u32_e32 v150, vcc, 0x1000, v150
	v_fmac_f32_e32 v74, v116, v68
	s_nop 0
	v_addc_co_u32_e32 v151, vcc, 0, v151, vcc
	global_load_ushort v79, v[150:151], off offset:1536
	v_mad_i64_i32 v[150:151], s[22:23], v80, s33, v[112:113]
	v_lshl_add_u64 v[150:151], v[150:151], 0, v[192:193]
	v_add_co_u32_e32 v150, vcc, 0x1000, v150
	v_mad_i64_i32 v[80:81], s[22:23], v81, s33, v[112:113]
	s_nop 0
	v_addc_co_u32_e32 v151, vcc, 0, v151, vcc
	v_lshl_add_u64 v[80:81], v[80:81], 0, v[192:193]
	v_add_co_u32_e32 v80, vcc, 0x1000, v80
	global_load_ushort v83, v[150:151], off offset:1536
	s_nop 0
	v_addc_co_u32_e32 v81, vcc, 0, v81, vcc
	global_load_ushort v85, v[80:81], off offset:1536
	v_mad_i64_i32 v[80:81], s[22:23], v84, s33, v[112:113]
	v_lshl_add_u64 v[80:81], v[80:81], 0, v[192:193]
	v_add_co_u32_e32 v80, vcc, 0x1000, v80
	v_fma_f32 v84, v115, v66, v119
	s_nop 0
	v_addc_co_u32_e32 v81, vcc, 0, v81, vcc
	global_load_ushort v89, v[80:81], off offset:1536
	v_mad_i64_i32 v[80:81], s[22:23], v86, s33, v[112:113]
	v_lshl_add_u64 v[80:81], v[80:81], 0, v[192:193]
	v_add_co_u32_e32 v80, vcc, 0x1000, v80
	v_fmac_f32_e32 v84, v116, v69
	s_nop 0
	v_addc_co_u32_e32 v81, vcc, 0, v81, vcc
	global_load_ushort v91, v[80:81], off offset:1536
	v_mad_i64_i32 v[80:81], s[22:23], v92, s33, v[112:113]
	v_lshl_add_u64 v[80:81], v[80:81], 0, v[192:193]
	v_add_co_u32_e32 v80, vcc, 0x1000, v80
	v_fmac_f32_e32 v84, v117, v68
	s_nop 0
	v_addc_co_u32_e32 v81, vcc, 0, v81, vcc
	global_load_ushort v95, v[80:81], off offset:1536
	v_mad_i64_i32 v[80:81], s[22:23], v87, s33, v[112:113]
	v_lshl_add_u64 v[80:81], v[80:81], 0, v[192:193]
	v_add_co_u32_e32 v80, vcc, 0x1000, v80
	v_fmac_f32_e32 v84, v118, v72
	s_nop 0
	v_addc_co_u32_e32 v81, vcc, 0, v81, vcc
	global_load_ushort v97, v[80:81], off offset:1536
	v_mad_i64_i32 v[80:81], s[22:23], v93, s33, v[112:113]
	v_lshl_add_u64 v[80:81], v[80:81], 0, v[192:193]
	v_add_co_u32_e32 v80, vcc, 0x1000, v80
	v_fmac_f32_e32 v74, v117, v72
	s_nop 0
	v_addc_co_u32_e32 v81, vcc, 0, v81, vcc
	global_load_ushort v101, v[80:81], off offset:1536
	v_mad_i64_i32 v[80:81], s[22:23], v98, s33, v[112:113]
	v_lshl_add_u64 v[80:81], v[80:81], 0, v[192:193]
	v_add_co_u32_e32 v80, vcc, 0x1000, v80
	v_fmac_f32_e32 v74, v118, v70
	s_nop 0
	v_addc_co_u32_e32 v81, vcc, 0, v81, vcc
	global_load_ushort v107, v[80:81], off offset:1536
	v_mad_i64_i32 v[80:81], s[22:23], v99, s33, v[112:113]
	v_lshl_add_u64 v[80:81], v[80:81], 0, v[192:193]
	v_add_co_u32_e32 v80, vcc, 0x1000, v80
	v_fma_f32 v87, v115, v70, v119
	s_nop 0
	v_addc_co_u32_e32 v81, vcc, 0, v81, vcc
	global_load_ushort v103, v[80:81], off offset:1536
	v_mad_i64_i32 v[80:81], s[22:23], v104, s33, v[112:113]
	v_lshl_add_u64 v[80:81], v[80:81], 0, v[192:193]
	v_add_co_u32_e32 v80, vcc, 0x1000, v80
	v_fmac_f32_e32 v87, v116, v76
	s_nop 0
	v_addc_co_u32_e32 v81, vcc, 0, v81, vcc
	global_load_ushort v109, v[80:81], off offset:1536
	v_mad_i64_i32 v[80:81], s[22:23], v105, s33, v[112:113]
	v_lshl_add_u64 v[80:81], v[80:81], 0, v[192:193]
	v_add_co_u32_e32 v80, vcc, 0x1000, v80
	v_fma_f32 v86, v115, v76, v119
	s_nop 0
	v_addc_co_u32_e32 v81, vcc, 0, v81, vcc
	global_load_ushort v111, v[80:81], off offset:1536
	v_mad_i64_i32 v[80:81], s[22:23], v108, s33, v[112:113]
	v_lshl_add_u64 v[80:81], v[80:81], 0, v[192:193]
	v_add_co_u32_e32 v80, vcc, 0x1000, v80
	v_fma_f32 v108, v115, v65, v119
	s_nop 0
	v_addc_co_u32_e32 v81, vcc, 0, v81, vcc
	global_load_ushort v150, v[80:81], off offset:1536
	v_mad_i64_i32 v[80:81], s[22:23], v110, s33, v[112:113]
	v_fma_f32 v110, v115, v64, v119
	v_lshl_add_u64 v[80:81], v[80:81], 0, v[192:193]
	v_fmac_f32_e32 v110, v116, v67
	v_fma_f32 v112, v115, v67, v119
; #define LAS __attribute__((address_space(3)))
; __device__ __forceinline__ float bf2f(bf16 b) { return __uint_as_float((unsigned)b << 16); }
; __device__ __forceinline__ bf16 f2bf_hw(float x) { return (bf16)(pk2(x, x) & 0xffffu); }
; __device__ __forceinline__ f32x4 mfma16(bf16x8 a, bf16x8 b, f32x4 c) { return __builtin_amdgcn_mfma_f32_16x16x32_bf16(a, b, c, 0, 0, 0); }
;     __device__ __forceinline__ int nt(const Unit& u, int) const { return (u.pn >> 2) == 0 ? 4 : 8; }
; __device__ __forceinline__ void lru_unit(const Ctx& C, const Params& p, int l, int unit) {
;     ...
;         for (int i = 0; i < 16; ++i) gbv[i] = bf2f(Zb[(size_t)(t0 + i) * ZC + GB + ch]);
; #pragma unroll
;         for (int i = 0; i < 16; ++i) { xc[i] = cb + cw0 * xw[i] + cw1 * xw[i + 1] + cw2 * xw[i + 2] + cw3 * xw[i + 3];
;             *(LAS bf16*)(XCB + (16 * tg + i) * 144 + c * 2) = f2bf_hw(xc[i]); }
;         __syncthreads();
;         {
;             const LAS unsigned char* ap = XCB + (16 * C.wave + i16) * 144 + 16 * g;
;             const bf16x8 a0 = *(const LAS bf16x8*)ap, a1 = *(const LAS bf16x8*)(ap + 64);
; #pragma unroll
;             for (int nt = 0; nt < 4; ++nt) {
;                 f32x4 r = mfma16(a0, wa[nt][0], (f32x4){0.f, 0.f, 0.f, 0.f}); r = mfma16(a1, wa[nt][1], r);
;                 f32x4 x = mfma16(a0, wx[nt][0], (f32x4){0.f, 0.f, 0.f, 0.f}); x = mfma16(a1, wx[nt][1], x);
; #pragma unroll
;                 for (int jj = 0; jj < 4; ++jj) { RF[(16 * C.wave + 4 * g + jj) * 64 + 16 * nt + i16] = r[jj]; IF[(16 * C.wave + 4 * g + jj) * 64 + 16 * nt + i16] = x[jj]; }
;             }
;         }
;         __syncthreads();
	v_add_co_u32_e32 v80, vcc, 0x1000, v80
	v_fmac_f32_e32 v110, v117, v66
	v_fmac_f32_e32 v112, v116, v66
	v_addc_co_u32_e32 v81, vcc, 0, v81, vcc
	v_fmac_f32_e32 v110, v118, v69
	v_fmac_f32_e32 v112, v117, v69
	global_load_ushort v151, v[80:81], off offset:1536
	v_fmac_f32_e32 v108, v116, v64
	v_cvt_pk_bf16_f32 v64, v110, s0
	v_fmac_f32_e32 v112, v118, v68
	v_fma_f32 v81, v115, v68, v119
	ds_write_b16 v131, v64 offset:64
	v_cvt_pk_bf16_f32 v64, v112, s0
	v_fmac_f32_e32 v81, v116, v72
	v_fma_f32 v80, v115, v72, v119
	ds_write_b16 v131, v64 offset:208
	v_cvt_pk_bf16_f32 v64, v84, s0
	v_fmac_f32_e32 v81, v117, v70
	v_fmac_f32_e32 v80, v116, v70
	ds_write_b16 v131, v64 offset:352
	v_cvt_pk_bf16_f32 v64, v74, s0
	v_fmac_f32_e32 v81, v118, v76
	v_fmac_f32_e32 v80, v117, v76
	ds_write_b16 v131, v64 offset:496
	v_cvt_pk_bf16_f32 v64, v81, s0
	v_fmac_f32_e32 v80, v118, v75
	v_fmac_f32_e32 v87, v117, v75
	v_fmac_f32_e32 v86, v116, v75
	v_fma_f32 v93, v115, v75, v119
	ds_write_b16 v131, v64 offset:640
	v_cvt_pk_bf16_f32 v64, v80, s0
	v_fmac_f32_e32 v87, v118, v82
	v_fmac_f32_e32 v86, v117, v82
	v_fmac_f32_e32 v93, v116, v82
	v_fma_f32 v92, v115, v82, v119
	ds_write_b16 v131, v64 offset:784
	v_cvt_pk_bf16_f32 v64, v87, s0
	v_fmac_f32_e32 v86, v118, v78
	v_fmac_f32_e32 v93, v117, v78
	v_fmac_f32_e32 v92, v116, v78
	v_fma_f32 v99, v115, v78, v119
	ds_write_b16 v131, v64 offset:928
	v_cvt_pk_bf16_f32 v64, v86, s0
	v_fmac_f32_e32 v93, v118, v90
	v_fmac_f32_e32 v92, v117, v90
	v_fmac_f32_e32 v99, v116, v90
	v_fma_f32 v98, v115, v90, v119
	ds_write_b16 v131, v64 offset:1072
	v_cvt_pk_bf16_f32 v64, v93, s0
	v_fmac_f32_e32 v92, v118, v88
	v_fmac_f32_e32 v99, v117, v88
	v_fmac_f32_e32 v98, v116, v88
	v_fma_f32 v105, v115, v88, v119
	ds_write_b16 v131, v64 offset:1216
	v_cvt_pk_bf16_f32 v64, v92, s0
	v_fmac_f32_e32 v99, v118, v96
	v_fmac_f32_e32 v98, v117, v96
	v_fmac_f32_e32 v105, v116, v96
	v_fma_f32 v104, v115, v96, v119
	v_fmac_f32_e32 v108, v117, v67
	ds_write_b16 v131, v64 offset:1360
	v_cvt_pk_bf16_f32 v64, v99, s0
	v_fmac_f32_e32 v98, v118, v94
	v_fmac_f32_e32 v105, v117, v94
	v_fmac_f32_e32 v104, v116, v94
	v_fma_f32 v67, v115, v94, v119
	ds_write_b16 v131, v64 offset:1504
	v_cvt_pk_bf16_f32 v64, v98, s0
	v_fmac_f32_e32 v105, v118, v102
	v_fmac_f32_e32 v104, v117, v102
	v_fmac_f32_e32 v67, v116, v102
	ds_write_b16 v131, v64 offset:1648
	v_cvt_pk_bf16_f32 v64, v105, s0
	v_fmac_f32_e32 v104, v118, v100
	v_fmac_f32_e32 v67, v117, v100
	v_fmac_f32_e32 v108, v118, v66
	ds_write_b16 v131, v64 offset:1792
	v_cvt_pk_bf16_f32 v64, v104, s0
	v_fmac_f32_e32 v67, v118, v106
	v_cvt_pk_bf16_f32 v65, v108, s0
	ds_write_b16 v131, v64 offset:1936
	v_cvt_pk_bf16_f32 v64, v67, s0
	ds_write_b16 v130, v65 offset:64
	ds_write_b16 v131, v64 offset:2080
	s_waitcnt lgkmcnt(0)
	s_barrier
	ds_read_b128 v[152:155], v133 offset:64
	ds_read_b128 v[156:159], v133 offset:128
	s_waitcnt vmcnt(31) lgkmcnt(1)
	v_mfma_f32_16x16x32_bf16 v[160:163], v[152:155], v[0:3], 0
	v_add_u32_e32 v64, 0x4800, v134
	v_add_u32_e32 v65, 0xc800, v134
	s_waitcnt vmcnt(29)
	v_mfma_f32_16x16x32_bf16 v[164:167], v[152:155], v[8:11], 0
	s_waitcnt vmcnt(27)
	v_mfma_f32_16x16x32_bf16 v[170:173], v[152:155], v[16:19], 0
	s_waitcnt vmcnt(25)
	v_mfma_f32_16x16x32_bf16 v[174:177], v[152:155], v[24:27], 0
	s_waitcnt lgkmcnt(0)
	v_mfma_f32_16x16x32_bf16 v[160:163], v[156:159], v[4:7], v[160:163]
	v_mfma_f32_16x16x32_bf16 v[164:167], v[156:159], v[12:15], v[164:167]
	v_mfma_f32_16x16x32_bf16 v[170:173], v[156:159], v[20:23], v[170:173]
	s_waitcnt vmcnt(24)
	v_mfma_f32_16x16x32_bf16 v[174:177], v[156:159], v[28:31], v[174:177]
	s_nop 5
	ds_write2_b32 v64, v160, v170 offset0:16 offset1:32
	s_nop 0
	ds_write2_b32 v65, v164, v174 offset0:16 offset1:32
	ds_write2_b32 v64, v161, v171 offset0:80 offset1:96
	ds_write2_b32 v65, v165, v175 offset0:80 offset1:96
	ds_write2_b32 v64, v162, v172 offset0:144 offset1:160
	ds_write2_b32 v65, v166, v176 offset0:144 offset1:160
	ds_write2_b32 v64, v163, v173 offset0:208 offset1:224
	ds_write2_b32 v65, v167, v177 offset0:208 offset1:224
	s_waitcnt vmcnt(23)
	v_mfma_f32_16x16x32_bf16 v[160:163], v[152:155], v[32:35], 0
	s_waitcnt vmcnt(19)
	v_mfma_f32_16x16x32_bf16 v[170:173], v[152:155], v[48:51], 0
	v_mfma_f32_16x16x32_bf16 v[164:167], v[152:155], v[40:43], 0
	s_waitcnt vmcnt(17)
	v_mfma_f32_16x16x32_bf16 v[152:155], v[152:155], v[56:59], 0
	v_mfma_f32_16x16x32_bf16 v[160:163], v[156:159], v[36:39], v[160:163]
	v_mfma_f32_16x16x32_bf16 v[170:173], v[156:159], v[52:55], v[170:173]
	v_mfma_f32_16x16x32_bf16 v[164:167], v[156:159], v[44:47], v[164:167]
	s_waitcnt vmcnt(16)
	v_mfma_f32_16x16x32_bf16 v[152:155], v[156:159], v[60:63], v[152:155]
	s_nop 4
	ds_write2_b32 v64, v160, v170 offset0:48 offset1:64
	s_nop 1
	ds_write2_b32 v65, v164, v152 offset0:48 offset1:64
	ds_write2_b32 v64, v161, v171 offset0:112 offset1:128
	ds_write2_b32 v65, v165, v153 offset0:112 offset1:128
	ds_write2_b32 v64, v162, v172 offset0:176 offset1:192
	ds_write2_b32 v65, v166, v154 offset0:176 offset1:192
	v_add_u32_e32 v64, 0x4a00, v134
	ds_write2_b32 v64, v163, v173 offset0:112 offset1:128
	v_add_u32_e32 v64, 0xca00, v134
	ds_write2_b32 v64, v167, v155 offset0:112 offset1:128
	v_add_u32_e32 v64, 64, v128
	s_waitcnt lgkmcnt(0)
	s_barrier
; __device__ __forceinline__ float sigmoidf_(float x) { return __builtin_amdgcn_rcpf(1.0f + __expf(-x)); }
; __device__ __forceinline__ void lru_unit(const Ctx& C, const Params& p, int l, int unit) {
;     ...
;         float av[16], bt[16]; float Ap = 1.f, hl = 0.f;
; #pragma unroll
;         for (int i = 0; i < 16; ++i) {
;             const float r = sigmoidf_(RF[(16 * tg + i) * 64 + c] + ba), ig = sigmoidf_(IF[(16 * tg + i) * 64 + c] + bx);
;             const float la = r * logu; av[i] = __expf(la);
;             const float x2 = 2.0f * la;
;             const float em = -x2 * (1.0f + x2 * (0.5f + x2 * (0.16666667f + x2 * (0.041666668f + x2 * (0.0083333338f + x2 * 0.0013888889f)))));
;             bt[i] = __builtin_amdgcn_sqrtf(em) * (ig * xc[i]);
;             Ap *= av[i]; hl = av[i] * hl + bt[i];
;         }
	ds_read2st64_b32 v[64:65], v64 offset0:72 offset1:200
	s_waitcnt lgkmcnt(0)
	v_add_f32_e32 v64, v120, v64
	v_mul_f32_e32 v64, 0xbfb8aa3b, v64
	v_exp_f32_e32 v64, v64
	v_add_f32_e32 v65, v121, v65
	v_mul_f32_e32 v65, 0xbfb8aa3b, v65
	v_exp_f32_e32 v65, v65
	v_add_f32_e32 v64, 1.0, v64
	v_rcp_f32_e32 v64, v64
	v_add_f32_e32 v65, 1.0, v65
	v_rcp_f32_e32 v66, v65
	v_mul_f32_e32 v64, v124, v64
	v_mul_f32_e32 v65, 0x3fb8aa3b, v64
	v_add_f32_e32 v64, v64, v64
	v_fmamk_f32 v68, v64, 0x3ab60b61, v234
	v_fmaak_f32 v68, v64, v68, 0x3d2aaaab
	v_fmaak_f32 v68, v64, v68, 0x3e2aaaab
	v_fma_f32 v68, v64, v68, 0.5
	v_fma_f32 v68, v64, v68, 1.0
	v_mul_f32_e64 v64, v68, -v64
	ds_read2st64_b32 v[68:69], v135 offset0:72 offset1:200
	v_sqrt_f32_e32 v64, v64
	v_mul_f32_e32 v66, v108, v66
	v_exp_f32_e32 v65, v65
	v_mul_f32_e32 v66, v66, v64
	s_waitcnt lgkmcnt(0)
	v_add_f32_e32 v64, v120, v68
	v_mul_f32_e32 v64, 0xbfb8aa3b, v64
	v_exp_f32_e32 v64, v64
	v_add_f32_e32 v68, v121, v69
	v_mul_f32_e32 v68, 0xbfb8aa3b, v68
	v_exp_f32_e32 v68, v68
	v_add_f32_e32 v64, 1.0, v64
	v_rcp_f32_e32 v64, v64
	v_fma_f32 v72, 0, v65, v66
	v_add_f32_e32 v68, 1.0, v68
	v_rcp_f32_e32 v68, v68
	v_mul_f32_e32 v69, v124, v64
	v_mul_f32_e32 v64, 0x3fb8aa3b, v69
	v_add_f32_e32 v69, v69, v69
	v_fmamk_f32 v70, v69, 0x3ab60b61, v234
	v_fmaak_f32 v70, v69, v70, 0x3d2aaaab
	v_fmaak_f32 v70, v69, v70, 0x3e2aaaab
	v_fma_f32 v70, v69, v70, 0.5
	v_fma_f32 v70, v69, v70, 1.0
	v_mul_f32_e64 v69, v70, -v69
	v_sqrt_f32_e32 v69, v69
	v_mul_f32_e32 v68, v110, v68
	v_exp_f32_e32 v64, v64
	v_mul_f32_e32 v70, v68, v69
	ds_read2st64_b32 v[68:69], v136 offset0:72 offset1:200
	v_fma_f32 v76, v64, v72, v70
	v_mul_f32_e32 v75, v65, v64
	s_waitcnt lgkmcnt(0)
	v_add_f32_e32 v68, v120, v68
	v_mul_f32_e32 v68, 0xbfb8aa3b, v68
	v_exp_f32_e32 v68, v68
	v_add_f32_e32 v69, v121, v69
	v_mul_f32_e32 v69, 0xbfb8aa3b, v69
	v_exp_f32_e32 v69, v69
	v_add_f32_e32 v68, 1.0, v68
	v_rcp_f32_e32 v68, v68
	v_add_f32_e32 v69, 1.0, v69
	v_rcp_f32_e32 v72, v69
	v_mul_f32_e32 v68, v124, v68
	v_mul_f32_e32 v69, 0x3fb8aa3b, v68
	v_add_f32_e32 v68, v68, v68
	v_fmamk_f32 v78, v68, 0x3ab60b61, v234
	v_fmaak_f32 v78, v68, v78, 0x3d2aaaab
	v_fmaak_f32 v78, v68, v78, 0x3e2aaaab
	v_fma_f32 v78, v68, v78, 0.5
	v_fma_f32 v78, v68, v78, 1.0
	v_mul_f32_e64 v68, v78, -v68
	v_mul_f32_e32 v72, v112, v72
	ds_read2st64_b32 v[112:113], v137 offset0:72 offset1:200
	v_sqrt_f32_e32 v68, v68
	v_exp_f32_e32 v69, v69
	v_mul_f32_e32 v72, v72, v68
	s_waitcnt lgkmcnt(0)
	v_add_f32_e32 v68, v120, v112
	v_mul_f32_e32 v68, 0xbfb8aa3b, v68
	v_exp_f32_e32 v68, v68
	v_fma_f32 v78, v69, v76, v72
	v_add_f32_e32 v76, v121, v113
	v_mul_f32_e32 v76, 0xbfb8aa3b, v76
	v_add_f32_e32 v68, 1.0, v68
	v_rcp_f32_e32 v68, v68
	v_exp_f32_e32 v76, v76
	ds_read2st64_b32 v[112:113], v138 offset0:72 offset1:200
	v_mul_f32_e32 v75, v75, v69
	v_mul_f32_e32 v82, v124, v68
	v_mul_f32_e32 v68, 0x3fb8aa3b, v82
	v_add_f32_e32 v82, v82, v82
	v_fmamk_f32 v88, v82, 0x3ab60b61, v234
	v_fmaak_f32 v88, v82, v88, 0x3d2aaaab
	v_fmaak_f32 v88, v82, v88, 0x3e2aaaab
	v_fma_f32 v88, v82, v88, 0.5
	v_add_f32_e32 v76, 1.0, v76
	v_fma_f32 v88, v82, v88, 1.0
	v_rcp_f32_e32 v76, v76
	v_mul_f32_e64 v82, v88, -v82
	v_exp_f32_e32 v68, v68
	v_sqrt_f32_e32 v82, v82
	v_mul_f32_e32 v76, v84, v76
	v_mul_f32_e32 v76, v76, v82
	v_mul_f32_e32 v82, v75, v68
	s_waitcnt lgkmcnt(0)
	v_add_f32_e32 v75, v120, v112
	v_mul_f32_e32 v75, 0xbfb8aa3b, v75
	v_exp_f32_e32 v75, v75
	v_fma_f32 v84, v68, v78, v76
	v_add_f32_e32 v78, v121, v113
	v_mul_f32_e32 v78, 0xbfb8aa3b, v78
	v_add_f32_e32 v75, 1.0, v75
	v_rcp_f32_e32 v75, v75
	v_exp_f32_e32 v78, v78
	ds_read2st64_b32 v[112:113], v139 offset0:72 offset1:200
	v_mul_f32_e32 v88, v124, v75
	v_mul_f32_e32 v75, 0x3fb8aa3b, v88
	v_add_f32_e32 v88, v88, v88
	v_fmamk_f32 v90, v88, 0x3ab60b61, v234
	v_fmaak_f32 v90, v88, v90, 0x3d2aaaab
	v_fmaak_f32 v90, v88, v90, 0x3e2aaaab
	v_fma_f32 v90, v88, v90, 0.5
	v_add_f32_e32 v78, 1.0, v78
	v_fma_f32 v90, v88, v90, 1.0
	v_rcp_f32_e32 v78, v78
	v_mul_f32_e64 v88, v90, -v88
	v_sqrt_f32_e32 v88, v88
	v_exp_f32_e32 v75, v75
	v_mul_f32_e32 v74, v74, v78
	v_mul_f32_e32 v78, v74, v88
	s_waitcnt lgkmcnt(0)
	v_add_f32_e32 v74, v120, v112
	v_mul_f32_e32 v74, 0xbfb8aa3b, v74
	v_exp_f32_e32 v74, v74
	v_mul_f32_e32 v88, v82, v75
	v_add_f32_e32 v82, v121, v113
	v_mul_f32_e32 v82, 0xbfb8aa3b, v82
	v_add_f32_e32 v74, 1.0, v74
	v_rcp_f32_e32 v74, v74
	v_exp_f32_e32 v82, v82
	ds_read2st64_b32 v[112:113], v140 offset0:72 offset1:200
	v_fma_f32 v84, v75, v84, v78
	v_mul_f32_e32 v90, v124, v74
	v_mul_f32_e32 v74, 0x3fb8aa3b, v90
	v_add_f32_e32 v90, v90, v90
	v_fmamk_f32 v94, v90, 0x3ab60b61, v234
	v_fmaak_f32 v94, v90, v94, 0x3d2aaaab
	v_fmaak_f32 v94, v90, v94, 0x3e2aaaab
	v_fma_f32 v94, v90, v94, 0.5
	v_add_f32_e32 v82, 1.0, v82
	v_fma_f32 v94, v90, v94, 1.0
	v_rcp_f32_e32 v82, v82
	v_mul_f32_e64 v90, v94, -v90
	v_sqrt_f32_e32 v90, v90
	v_exp_f32_e32 v74, v74
	v_mul_f32_e32 v81, v81, v82
	v_mul_f32_e32 v82, v81, v90
	s_waitcnt lgkmcnt(0)
	v_add_f32_e32 v81, v120, v112
	v_mul_f32_e32 v81, 0xbfb8aa3b, v81
	v_exp_f32_e32 v81, v81
	v_fma_f32 v90, v74, v84, v82
	v_add_f32_e32 v84, v121, v113
	v_mul_f32_e32 v84, 0xbfb8aa3b, v84
	v_add_f32_e32 v81, 1.0, v81
	v_rcp_f32_e32 v81, v81
	v_exp_f32_e32 v84, v84
	ds_read2st64_b32 v[112:113], v141 offset0:72 offset1:200
	v_mul_f32_e32 v88, v88, v74
	v_mul_f32_e32 v94, v124, v81
	v_mul_f32_e32 v81, 0x3fb8aa3b, v94
	v_add_f32_e32 v94, v94, v94
	v_fmamk_f32 v96, v94, 0x3ab60b61, v234
	v_fmaak_f32 v96, v94, v96, 0x3d2aaaab
	v_fmaak_f32 v96, v94, v96, 0x3e2aaaab
	v_fma_f32 v96, v94, v96, 0.5
	v_add_f32_e32 v84, 1.0, v84
	v_fma_f32 v96, v94, v96, 1.0
	v_rcp_f32_e32 v84, v84
	v_mul_f32_e64 v94, v96, -v94
	v_sqrt_f32_e32 v94, v94
	v_exp_f32_e32 v81, v81
	v_mul_f32_e32 v80, v80, v84
	v_mul_f32_e32 v84, v80, v94
	s_waitcnt lgkmcnt(0)
; __device__ __forceinline__ float sigmoidf_(float x) { return __builtin_amdgcn_rcpf(1.0f + __expf(-x)); }
; __device__ __forceinline__ void lru_unit(const Ctx& C, const Params& p, int l, int unit) {
;     ...
;         float av[16], bt[16]; float Ap = 1.f, hl = 0.f;
; #pragma unroll
;         for (int i = 0; i < 16; ++i) {
;             const float r = sigmoidf_(RF[(16 * tg + i) * 64 + c] + ba), ig = sigmoidf_(IF[(16 * tg + i) * 64 + c] + bx);
;             const float la = r * logu; av[i] = __expf(la);
;             const float x2 = 2.0f * la;
;             const float em = -x2 * (1.0f + x2 * (0.5f + x2 * (0.16666667f + x2 * (0.041666668f + x2 * (0.0083333338f + x2 * 0.0013888889f)))));
;             bt[i] = __builtin_amdgcn_sqrtf(em) * (ig * xc[i]);
;             Ap *= av[i]; hl = av[i] * hl + bt[i];
;         }
	v_add_f32_e32 v80, v120, v112
	v_mul_f32_e32 v80, 0xbfb8aa3b, v80
	v_exp_f32_e32 v80, v80
	v_mul_f32_e32 v94, v88, v81
	v_add_f32_e32 v88, v121, v113
	v_mul_f32_e32 v88, 0xbfb8aa3b, v88
	v_add_f32_e32 v80, 1.0, v80
	v_rcp_f32_e32 v80, v80
	v_exp_f32_e32 v88, v88
	ds_read2st64_b32 v[112:113], v142 offset0:72 offset1:200
	v_fma_f32 v90, v81, v90, v84
	v_mul_f32_e32 v96, v124, v80
	v_mul_f32_e32 v80, 0x3fb8aa3b, v96
	v_add_f32_e32 v96, v96, v96
	v_fmamk_f32 v100, v96, 0x3ab60b61, v234
	v_fmaak_f32 v100, v96, v100, 0x3d2aaaab
	v_fmaak_f32 v100, v96, v100, 0x3e2aaaab
	v_fma_f32 v100, v96, v100, 0.5
	v_add_f32_e32 v88, 1.0, v88
	v_fma_f32 v100, v96, v100, 1.0
	v_rcp_f32_e32 v88, v88
	v_mul_f32_e64 v96, v100, -v96
	v_sqrt_f32_e32 v96, v96
	v_exp_f32_e32 v80, v80
	v_mul_f32_e32 v87, v87, v88
	v_mul_f32_e32 v88, v87, v96
	s_waitcnt lgkmcnt(0)
	v_add_f32_e32 v87, v120, v112
	v_mul_f32_e32 v87, 0xbfb8aa3b, v87
	v_exp_f32_e32 v87, v87
	v_fma_f32 v96, v80, v90, v88
	v_add_f32_e32 v90, v121, v113
	v_mul_f32_e32 v90, 0xbfb8aa3b, v90
	v_add_f32_e32 v87, 1.0, v87
	v_rcp_f32_e32 v87, v87
	v_exp_f32_e32 v90, v90
	ds_read2st64_b32 v[112:113], v143 offset0:72 offset1:200
	v_mul_f32_e32 v94, v94, v80
	v_mul_f32_e32 v100, v124, v87
	v_mul_f32_e32 v87, 0x3fb8aa3b, v100
	v_add_f32_e32 v100, v100, v100
	v_fmamk_f32 v102, v100, 0x3ab60b61, v234
	v_fmaak_f32 v102, v100, v102, 0x3d2aaaab
	v_fmaak_f32 v102, v100, v102, 0x3e2aaaab
	v_fma_f32 v102, v100, v102, 0.5
	v_add_f32_e32 v90, 1.0, v90
	v_fma_f32 v102, v100, v102, 1.0
	v_rcp_f32_e32 v90, v90
	v_mul_f32_e64 v100, v102, -v100
	v_sqrt_f32_e32 v100, v100
	v_exp_f32_e32 v87, v87
	v_mul_f32_e32 v86, v86, v90
	v_mul_f32_e32 v90, v86, v100
	s_waitcnt lgkmcnt(0)
	v_add_f32_e32 v86, v120, v112
	v_mul_f32_e32 v86, 0xbfb8aa3b, v86
	v_exp_f32_e32 v86, v86
	v_mul_f32_e32 v100, v94, v87
	v_add_f32_e32 v94, v121, v113
	v_mul_f32_e32 v94, 0xbfb8aa3b, v94
	v_add_f32_e32 v86, 1.0, v86
	v_rcp_f32_e32 v86, v86
	v_exp_f32_e32 v94, v94
	ds_read2st64_b32 v[112:113], v144 offset0:72 offset1:200
	v_fma_f32 v96, v87, v96, v90
	v_mul_f32_e32 v102, v124, v86
	v_mul_f32_e32 v86, 0x3fb8aa3b, v102
	v_add_f32_e32 v102, v102, v102
	v_fmamk_f32 v106, v102, 0x3ab60b61, v234
	v_fmaak_f32 v106, v102, v106, 0x3d2aaaab
	v_fmaak_f32 v106, v102, v106, 0x3e2aaaab
	v_fma_f32 v106, v102, v106, 0.5
	v_add_f32_e32 v94, 1.0, v94
	v_fma_f32 v106, v102, v106, 1.0
	v_rcp_f32_e32 v94, v94
	v_mul_f32_e64 v102, v106, -v102
	v_sqrt_f32_e32 v102, v102
	v_exp_f32_e32 v86, v86
	v_mul_f32_e32 v93, v93, v94
	v_mul_f32_e32 v94, v93, v102
	s_waitcnt lgkmcnt(0)
	v_add_f32_e32 v93, v120, v112
	v_mul_f32_e32 v93, 0xbfb8aa3b, v93
	v_exp_f32_e32 v93, v93
	v_fma_f32 v102, v86, v96, v94
	v_add_f32_e32 v96, v121, v113
	v_mul_f32_e32 v96, 0xbfb8aa3b, v96
	v_add_f32_e32 v93, 1.0, v93
	v_rcp_f32_e32 v93, v93
	v_exp_f32_e32 v96, v96
	ds_read2st64_b32 v[112:113], v145 offset0:72 offset1:200
	v_mul_f32_e32 v100, v100, v86
	v_mul_f32_e32 v106, v124, v93
	v_mul_f32_e32 v93, 0x3fb8aa3b, v106
	v_add_f32_e32 v106, v106, v106
	v_fmamk_f32 v108, v106, 0x3ab60b61, v234
	v_fmaak_f32 v108, v106, v108, 0x3d2aaaab
	v_fmaak_f32 v108, v106, v108, 0x3e2aaaab
	v_fma_f32 v108, v106, v108, 0.5
	v_add_f32_e32 v96, 1.0, v96
	v_fma_f32 v108, v106, v108, 1.0
	v_rcp_f32_e32 v96, v96
	v_mul_f32_e64 v106, v108, -v106
	v_sqrt_f32_e32 v106, v106
	v_exp_f32_e32 v93, v93
	v_mul_f32_e32 v92, v92, v96
	v_mul_f32_e32 v96, v92, v106
	s_waitcnt lgkmcnt(0)
	v_add_f32_e32 v92, v120, v112
	v_mul_f32_e32 v92, 0xbfb8aa3b, v92
	v_exp_f32_e32 v92, v92
	v_mul_f32_e32 v106, v100, v93
	v_add_f32_e32 v100, v121, v113
	v_mul_f32_e32 v100, 0xbfb8aa3b, v100
	v_add_f32_e32 v92, 1.0, v92
	v_rcp_f32_e32 v92, v92
	v_exp_f32_e32 v100, v100
	ds_read2st64_b32 v[112:113], v146 offset0:72 offset1:200
	v_fma_f32 v102, v93, v102, v96
	v_mul_f32_e32 v108, v124, v92
	v_mul_f32_e32 v92, 0x3fb8aa3b, v108
	v_add_f32_e32 v108, v108, v108
	v_fmamk_f32 v110, v108, 0x3ab60b61, v234
	v_fmaak_f32 v110, v108, v110, 0x3d2aaaab
	v_fmaak_f32 v110, v108, v110, 0x3e2aaaab
	v_fma_f32 v110, v108, v110, 0.5
	v_add_f32_e32 v100, 1.0, v100
	v_fma_f32 v110, v108, v110, 1.0
	v_rcp_f32_e32 v100, v100
	v_mul_f32_e64 v108, v110, -v108
	v_sqrt_f32_e32 v108, v108
	v_exp_f32_e32 v92, v92
	v_mul_f32_e32 v99, v99, v100
	v_mul_f32_e32 v100, v99, v108
	s_waitcnt lgkmcnt(0)
; __device__ __forceinline__ float sigmoidf_(float x) { return __builtin_amdgcn_rcpf(1.0f + __expf(-x)); }
; __device__ __forceinline__ void lru_unit(const Ctx& C, const Params& p, int l, int unit) {
;     ...
;         for (int i = 0; i < 16; ++i) {
;             const float r = sigmoidf_(RF[(16 * tg + i) * 64 + c] + ba), ig = sigmoidf_(IF[(16 * tg + i) * 64 + c] + bx);
;             const float la = r * logu; av[i] = __expf(la);
;             const float x2 = 2.0f * la;
;             const float em = -x2 * (1.0f + x2 * (0.5f + x2 * (0.16666667f + x2 * (0.041666668f + x2 * (0.0083333338f + x2 * 0.0013888889f)))));
;             bt[i] = __builtin_amdgcn_sqrtf(em) * (ig * xc[i]);
;             Ap *= av[i]; hl = av[i] * hl + bt[i];
;         }
;         AGG[(tg * 64 + c) * 2] = Ap; AGG[(tg * 64 + c) * 2 + 1] = hl;
;         __syncthreads();
;         float hcur = CAR[c], pcur = CARP[c];
;         for (int k = 0; k < tg; ++k) { const float ak = AGG[(k * 64 + c) * 2]; hcur = ak * hcur + AGG[(k * 64 + c) * 2 + 1]; pcur *= ak; }
	v_add_f32_e32 v99, v120, v112
	v_mul_f32_e32 v99, 0xbfb8aa3b, v99
	v_exp_f32_e32 v99, v99
	v_fma_f32 v108, v92, v102, v100
	v_add_f32_e32 v102, v121, v113
	v_mul_f32_e32 v102, 0xbfb8aa3b, v102
	v_add_f32_e32 v99, 1.0, v99
	v_rcp_f32_e32 v99, v99
	v_exp_f32_e32 v102, v102
	v_mul_f32_e32 v106, v106, v92
	v_mul_f32_e32 v110, v124, v99
	v_mul_f32_e32 v99, 0x3fb8aa3b, v110
	v_add_f32_e32 v110, v110, v110
	v_fmamk_f32 v112, v110, 0x3ab60b61, v234
	v_fmaak_f32 v112, v110, v112, 0x3d2aaaab
	v_fmaak_f32 v112, v110, v112, 0x3e2aaaab
	v_fma_f32 v112, v110, v112, 0.5
	v_add_f32_e32 v102, 1.0, v102
	v_fma_f32 v112, v110, v112, 1.0
	v_rcp_f32_e32 v102, v102
	v_mul_f32_e64 v110, v112, -v110
	ds_read2st64_b32 v[112:113], v147 offset0:72 offset1:200
	v_sqrt_f32_e32 v110, v110
	v_mul_f32_e32 v98, v98, v102
	v_exp_f32_e32 v99, v99
	v_mul_f32_e32 v102, v98, v110
	s_waitcnt lgkmcnt(0)
	v_add_f32_e32 v98, v120, v112
	v_mul_f32_e32 v98, 0xbfb8aa3b, v98
	v_exp_f32_e32 v98, v98
	v_mul_f32_e32 v110, v106, v99
	v_add_f32_e32 v106, v121, v113
	v_mul_f32_e32 v106, 0xbfb8aa3b, v106
	v_add_f32_e32 v98, 1.0, v98
	v_rcp_f32_e32 v98, v98
	v_exp_f32_e32 v106, v106
	v_fma_f32 v108, v99, v108, v102
	v_mul_f32_e32 v112, v124, v98
	v_mul_f32_e32 v98, 0x3fb8aa3b, v112
	v_add_f32_e32 v112, v112, v112
	v_fmamk_f32 v113, v112, 0x3ab60b61, v234
	v_fmaak_f32 v113, v112, v113, 0x3d2aaaab
	v_fmaak_f32 v113, v112, v113, 0x3e2aaaab
	v_fma_f32 v113, v112, v113, 0.5
	v_add_f32_e32 v106, 1.0, v106
	v_fma_f32 v113, v112, v113, 1.0
	v_rcp_f32_e32 v106, v106
	v_mul_f32_e64 v112, v113, -v112
	v_sqrt_f32_e32 v112, v112
	v_exp_f32_e32 v98, v98
	v_mul_f32_e32 v105, v105, v106
	v_mul_f32_e32 v106, v105, v112
	ds_read2st64_b32 v[112:113], v148 offset0:72 offset1:200
	v_fma_f32 v152, v98, v108, v106
	v_mul_f32_e32 v110, v110, v98
	s_waitcnt lgkmcnt(0)
	v_add_f32_e32 v105, v120, v112
	v_mul_f32_e32 v105, 0xbfb8aa3b, v105
	v_exp_f32_e32 v105, v105
	v_add_f32_e32 v108, v121, v113
	v_mul_f32_e32 v108, 0xbfb8aa3b, v108
	v_exp_f32_e32 v108, v108
	v_add_f32_e32 v105, 1.0, v105
	v_rcp_f32_e32 v105, v105
	v_add_f32_e32 v108, 1.0, v108
	v_rcp_f32_e32 v108, v108
	v_mul_f32_e32 v112, v124, v105
	v_mul_f32_e32 v105, 0x3fb8aa3b, v112
	v_add_f32_e32 v112, v112, v112
	v_fmamk_f32 v113, v112, 0x3ab60b61, v234
	v_fmaak_f32 v113, v112, v113, 0x3d2aaaab
	v_fmaak_f32 v113, v112, v113, 0x3e2aaaab
	v_fma_f32 v113, v112, v113, 0.5
	v_fma_f32 v113, v112, v113, 1.0
	v_mul_f32_e64 v112, v113, -v112
	v_sqrt_f32_e32 v112, v112
	v_mul_f32_e32 v104, v104, v108
	v_exp_f32_e32 v105, v105
	v_mul_f32_e32 v108, v104, v112
	ds_read2st64_b32 v[112:113], v149 offset0:72 offset1:200
	v_mul_f32_e32 v153, v110, v105
	v_fma_f32 v152, v105, v152, v108
	s_waitcnt lgkmcnt(0)
	v_add_f32_e32 v104, v120, v112
	v_mul_f32_e32 v104, 0xbfb8aa3b, v104
	v_exp_f32_e32 v104, v104
	v_add_f32_e32 v110, v121, v113
	v_mul_f32_e32 v110, 0xbfb8aa3b, v110
	v_exp_f32_e32 v110, v110
	v_add_f32_e32 v104, 1.0, v104
	v_rcp_f32_e32 v104, v104
	v_add_f32_e32 v110, 1.0, v110
	v_rcp_f32_e32 v110, v110
	v_mul_f32_e32 v112, v124, v104
	v_mul_f32_e32 v104, 0x3fb8aa3b, v112
	v_add_f32_e32 v112, v112, v112
	v_fmamk_f32 v113, v112, 0x3ab60b61, v234
	v_fmaak_f32 v113, v112, v113, 0x3d2aaaab
	v_fmaak_f32 v113, v112, v113, 0x3e2aaaab
	v_fma_f32 v113, v112, v113, 0.5
	v_fma_f32 v113, v112, v113, 1.0
	v_mul_f32_e64 v112, v113, -v112
	v_sqrt_f32_e32 v112, v112
	v_exp_f32_e32 v104, v104
	v_mul_f32_e32 v67, v67, v110
	v_mul_f32_e32 v110, v67, v112
	v_add_u32_e32 v67, 0, v122
	v_mul_f32_e32 v112, v153, v104
	v_fma_f32 v113, v104, v152, v110
	v_add_u32_e32 v67, 0x14840, v67
	ds_write_b64 v67, v[112:113]
	s_waitcnt lgkmcnt(0)
	s_barrier
	ds_read_b32 v113, v126
	ds_read_b32 v67, v127
	s_and_saveexec_b64 s[46:47], s[42:43]
	s_cbranch_execz .LBB0_369
	s_mov_b64 s[54:55], 0
	v_mov_b32_e32 v152, v129
	v_mov_b32_e32 v153, v123
